# the two prologue grid-barrier instances also use the hand-written protocol (wave-1 invalidate, monotonic counters, all blocks poll the top counter)
# speedup vs baseline: 1.0084x; 1.0084x over previous
.LBB0_79:
	s_cmp_lt_i32 s45, 2
	s_cbranch_scc1 .LBB0_129
	s_waitcnt vmcnt(0)
	s_barrier
	v_lshrrev_b32_e32 v0, 6, v128
	v_readfirstlane_b32 s20, v0
	s_cmp_lg_u32 s20, 1
	s_cbranch_scc1 .Lxb20_ninv
	buffer_inv sc1
.Lxb20_ninv:
	s_barrier
	s_mov_b64 s[0:1], exec
	v_readlane_b32 s2, v163, 17
	v_readlane_b32 s3, v163, 18
	s_and_b64 s[2:3], s[0:1], s[2:3]
	s_mov_b64 exec, s[2:3]
	s_cbranch_execz .LBB0_128
	v_mov_b32_e32 v16, 0
	s_waitcnt vmcnt(0) expcnt(0) lgkmcnt(0)
	ds_read_b32 v2, v16 offset:53248
	ds_read_b32 v0, v16 offset:53252
	s_waitcnt lgkmcnt(1)
	v_cmp_ne_u32_e32 vcc, 0, v2
	s_cbranch_vccnz .LBB0_96
	s_add_u32 s2, s84, 0x1000
	s_addc_u32 s3, s85, 0
	s_add_u32 s20, s84, 0x1100
	s_addc_u32 s21, s85, 0
	s_add_u32 s22, s84, 0x1200
	s_addc_u32 s23, s85, 0
	s_mul_i32 s34, s47, s33
	s_add_u32 s24, s84, 0x1300
	s_mul_i32 s34, s34, s46
	s_addc_u32 s25, s85, 0
	s_mov_b32 s35, 1
	s_branch .LBB0_84

.LBB0_96:
	s_waitcnt vmcnt(0) lgkmcnt(0)
	v_mov_b32_e32 v1, 0
	v_mov_b32_e32 v3, 1
	v_readlane_b32 s20, v162, 60
	s_lshl_b32 s2, s40, 8
	s_add_u32 s2, s84, s2
	s_addc_u32 s3, s85, 0
	s_add_u32 s2, s2, 0x1440
	s_addc_u32 s3, s3, 0
	s_add_u32 s20, s20, 1
	s_nop 2
	v_writelane_b32 v162, s20, 60
	global_atomic_add v4, v1, v3, s[2:3] sc0
	v_mul_lo_u32 v2, v2, s20
	v_mul_lo_u32 v0, v0, s20
	s_add_u32 s22, s84, 0x3440
	s_addc_u32 s23, s85, 0
	s_waitcnt vmcnt(0)
	v_add_u32_e32 v4, 1, v4
	s_nop 0
	v_cmp_eq_u32_e32 vcc, v4, v2
	s_nop 3
	s_cbranch_vccz .Lxb20_poll
	buffer_wbl2 sc1
	s_waitcnt vmcnt(0)
	global_atomic_add v1, v3, s[22:23]
.Lxb20_poll:
	s_mov_b32 s21, 0
.Lxb20_spin:
	global_load_dword v4, v1, s[22:23] sc1
	s_waitcnt vmcnt(0)
	v_cmp_ge_u32_e32 vcc, v4, v0
	s_cbranch_vccnz .Lxb20_done
	s_sleep 1
	s_add_u32 s21, s21, 1
	s_cmp_lt_u32 s21, 0x400000
	s_cbranch_scc1 .Lxb20_spin
.Lxb20_done:
.LBB0_128:
	s_or_b64 exec, exec, s[0:1]
	s_waitcnt vmcnt(0) lgkmcnt(0)
	s_barrier

.LBB0_135:
	s_or_b64 exec, exec, s[0:1]
	s_cmp_lt_u32 s45, 3
	s_cbranch_scc1 .LBB0_185
	s_waitcnt vmcnt(0)
	s_barrier
	v_lshrrev_b32_e32 v0, 6, v128
	v_readfirstlane_b32 s20, v0
	s_cmp_lg_u32 s20, 1
	s_cbranch_scc1 .Lxb21_ninv
	buffer_inv sc1
.Lxb21_ninv:
	s_barrier
	s_mov_b64 s[0:1], exec
	v_readlane_b32 s2, v163, 17
	v_readlane_b32 s3, v163, 18
	s_and_b64 s[2:3], s[0:1], s[2:3]
	s_mov_b64 exec, s[2:3]
	s_cbranch_execz .LBB0_184
	v_mov_b32_e32 v16, 0
	s_waitcnt vmcnt(0) expcnt(0) lgkmcnt(0)
	ds_read_b32 v2, v16 offset:53248
	ds_read_b32 v0, v16 offset:53252
	s_waitcnt lgkmcnt(1)
	v_cmp_ne_u32_e32 vcc, 0, v2
	s_cbranch_vccnz .LBB0_152
	s_add_u32 s2, s84, 0x1000
	s_addc_u32 s3, s85, 0
	s_add_u32 s20, s84, 0x1100
	s_addc_u32 s21, s85, 0
	s_add_u32 s22, s84, 0x1200
	s_addc_u32 s23, s85, 0
	s_mov_b32 s4, s34
	s_mul_i32 s34, s47, s33
	s_add_u32 s24, s84, 0x1300
	s_mul_i32 s34, s34, s46
	s_addc_u32 s25, s85, 0
	s_mov_b32 s35, 1
	s_branch .LBB0_140
